# GEMM K-loop: all 16 per-iteration LDS-DMA loads use scalar base + 32-bit lane offset; 16 64-bit VALU address adds per iteration removed, pointer registers no longer reused as LDS temporaries
# baseline (speedup 1.0000x reference)
.LBB0_246:
	s_andn2_b64 vcc, exec, s[18:19]
	s_cbranch_vccnz .Lk_zero_skip
	s_add_u32 s44, s44, 0x80
	s_addc_u32 s45, s45, 0
	s_add_u32 s23, s46, 0x100
	s_addc_u32 s48, s47, 0
	s_mov_b32 s46, 0
	s_add_i32 s49, s46, 2
	s_add_u32 s69, s44, 0x80
	s_addc_u32 s47, s45, 0
	s_add_i32 s80, 0, 0x10000
	s_cmp_eq_u32 s90, s46
	s_cselect_b32 s47, s65, s47
	s_cselect_b32 s46, s64, s69
	s_cselect_b32 s71, s67, s48
	s_cselect_b32 s70, s66, s23
	s_add_i32 s69, 0, 0x14000
	v_add_u32_e32 v140, s80, v227
	v_add_u32_e32 v152, s69, v227
	ds_read_b128 v[128:131], v140
	ds_read_b128 v[132:135], v140 offset:1024
	ds_read_b128 v[136:139], v140 offset:2048
	ds_read_b128 v[140:143], v140 offset:3072
	ds_read_b128 v[144:147], v152
	ds_read_b128 v[148:151], v152 offset:1024
	ds_read_b128 v[174:177], v152 offset:2048
	ds_read_b128 v[178:181], v152 offset:3072
	s_add_i32 m0, s50, 0xc000
	ds_read_b128 v[182:185], v230
	ds_read_b128 v[186:189], v230 offset:1024
	ds_read_b128 v[190:193], v230 offset:2048
	ds_read_b128 v[194:197], v230 offset:3072
	ds_read_b128 v[198:201], v230 offset:4096
	ds_read_b128 v[202:205], v230 offset:5120
	ds_read_b128 v[206:209], v230 offset:6144
	ds_read_b128 v[232:235], v230 offset:7168
	global_load_lds_dwordx4 v170, s[44:45]
	s_add_i32 m0, s50, 0xe000
	s_nop 0
	global_load_lds_dwordx4 v172, s[44:45]
	s_waitcnt vmcnt(8)
	s_waitcnt lgkmcnt(0)
	s_barrier
	s_setprio 1
	s_waitcnt lgkmcnt(0)
	v_mfma_f32_16x16x32_bf16 v[16:19], v[128:131], v[182:185], 0
	v_mfma_f32_16x16x32_bf16 v[28:31], v[136:139], v[182:185], 0
	v_mfma_f32_16x16x32_bf16 v[12:15], v[128:131], v[190:193], 0
	v_mfma_f32_16x16x32_bf16 v[8:11], v[136:139], v[190:193], 0
	v_mfma_f32_16x16x32_bf16 v[124:127], v[128:131], v[198:201], 0
	v_mfma_f32_16x16x32_bf16 v[120:123], v[136:139], v[198:201], 0
	v_mfma_f32_16x16x32_bf16 v[108:111], v[128:131], v[206:209], 0
	v_mfma_f32_16x16x32_bf16 v[104:107], v[136:139], v[206:209], 0
	v_mfma_f32_16x16x32_bf16 v[16:19], v[132:135], v[186:189], v[16:19]
	v_mfma_f32_16x16x32_bf16 v[28:31], v[140:143], v[186:189], v[28:31]
	v_mfma_f32_16x16x32_bf16 v[12:15], v[132:135], v[194:197], v[12:15]
	v_mfma_f32_16x16x32_bf16 v[8:11], v[140:143], v[194:197], v[8:11]
	v_mfma_f32_16x16x32_bf16 v[124:127], v[132:135], v[202:205], v[124:127]
	v_mfma_f32_16x16x32_bf16 v[120:123], v[140:143], v[202:205], v[120:123]
	v_mfma_f32_16x16x32_bf16 v[108:111], v[132:135], v[232:235], v[108:111]
	v_mfma_f32_16x16x32_bf16 v[104:107], v[140:143], v[232:235], v[104:107]
	s_setprio 0
	s_setprio 1
	v_mfma_f32_16x16x32_bf16 v[24:27], v[144:147], v[182:185], 0
	v_mfma_f32_16x16x32_bf16 v[20:23], v[174:177], v[182:185], 0
	v_mfma_f32_16x16x32_bf16 v[4:7], v[144:147], v[190:193], 0
	v_mfma_f32_16x16x32_bf16 v[0:3], v[174:177], v[190:193], 0
	v_mfma_f32_16x16x32_bf16 v[116:119], v[144:147], v[198:201], 0
	v_mfma_f32_16x16x32_bf16 v[112:115], v[174:177], v[198:201], 0
	v_mfma_f32_16x16x32_bf16 v[100:103], v[144:147], v[206:209], 0
	v_mfma_f32_16x16x32_bf16 v[96:99], v[174:177], v[206:209], 0
	v_mfma_f32_16x16x32_bf16 v[24:27], v[148:151], v[186:189], v[24:27]
	v_mfma_f32_16x16x32_bf16 v[20:23], v[178:181], v[186:189], v[20:23]
	v_mfma_f32_16x16x32_bf16 v[4:7], v[148:151], v[194:197], v[4:7]
	v_mfma_f32_16x16x32_bf16 v[0:3], v[178:181], v[194:197], v[0:3]
	v_mfma_f32_16x16x32_bf16 v[116:119], v[148:151], v[202:205], v[116:119]
	v_mfma_f32_16x16x32_bf16 v[112:115], v[178:181], v[202:205], v[112:115]
	v_mfma_f32_16x16x32_bf16 v[100:103], v[148:151], v[232:235], v[100:103]
	v_mfma_f32_16x16x32_bf16 v[96:99], v[178:181], v[232:235], v[96:99]
	s_setprio 0
	s_barrier
	s_add_i32 s80, s80, s3
	s_mov_b32 m0, s80
	ds_read_b128 v[182:185], v230 offset:16384
	ds_read_b128 v[186:189], v230 offset:17408
	ds_read_b128 v[190:193], v230 offset:18432
	ds_read_b128 v[194:197], v230 offset:19456
	ds_read_b128 v[198:201], v230 offset:20480
	ds_read_b128 v[202:205], v230 offset:21504
	ds_read_b128 v[206:209], v230 offset:22528
	ds_read_b128 v[232:235], v230 offset:23552
	global_load_lds_dwordx4 v160, s[70:71]
	s_add_i32 m0, s80, 0x2000
	s_add_i32 s69, s69, s3
	global_load_lds_dwordx4 v164, s[70:71]
	s_add_u32 s70, s70, s26
	s_addc_u32 s71, s71, 0
	s_mov_b32 m0, s69
	s_nop 0
	global_load_lds_dwordx4 v160, s[70:71]
	s_add_i32 m0, s69, 0x2000
	s_nop 0
	global_load_lds_dwordx4 v164, s[70:71]
	s_mov_b32 m0, s50
	s_nop 0
	global_load_lds_dwordx4 v158, s[46:47]
	s_mov_b32 m0, s51
	s_nop 0
	global_load_lds_dwordx4 v162, s[46:47]
	s_waitcnt vmcnt(8)
	s_waitcnt lgkmcnt(0)
	s_barrier
	s_setprio 1
	s_waitcnt lgkmcnt(0)
	v_mfma_f32_16x16x32_bf16 v[92:95], v[128:131], v[182:185], 0
	v_mfma_f32_16x16x32_bf16 v[88:91], v[136:139], v[182:185], 0
	v_mfma_f32_16x16x32_bf16 v[76:79], v[128:131], v[190:193], 0
	v_mfma_f32_16x16x32_bf16 v[72:75], v[136:139], v[190:193], 0
	v_mfma_f32_16x16x32_bf16 v[60:63], v[128:131], v[198:201], 0
	v_mfma_f32_16x16x32_bf16 v[56:59], v[136:139], v[198:201], 0
	v_mfma_f32_16x16x32_bf16 v[44:47], v[128:131], v[206:209], 0
	v_mfma_f32_16x16x32_bf16 v[40:43], v[136:139], v[206:209], 0
	v_mfma_f32_16x16x32_bf16 v[92:95], v[132:135], v[186:189], v[92:95]
	v_mfma_f32_16x16x32_bf16 v[88:91], v[140:143], v[186:189], v[88:91]
	v_mfma_f32_16x16x32_bf16 v[76:79], v[132:135], v[194:197], v[76:79]
	v_mfma_f32_16x16x32_bf16 v[72:75], v[140:143], v[194:197], v[72:75]
	v_mfma_f32_16x16x32_bf16 v[60:63], v[132:135], v[202:205], v[60:63]
	v_mfma_f32_16x16x32_bf16 v[56:59], v[140:143], v[202:205], v[56:59]
	v_mfma_f32_16x16x32_bf16 v[44:47], v[132:135], v[232:235], v[44:47]
	v_mfma_f32_16x16x32_bf16 v[40:43], v[140:143], v[232:235], v[40:43]
	s_setprio 0
	s_setprio 1
	v_mfma_f32_16x16x32_bf16 v[84:87], v[144:147], v[182:185], 0
	v_mfma_f32_16x16x32_bf16 v[80:83], v[174:177], v[182:185], 0
	v_mfma_f32_16x16x32_bf16 v[68:71], v[144:147], v[190:193], 0
	v_mfma_f32_16x16x32_bf16 v[64:67], v[174:177], v[190:193], 0
	v_mfma_f32_16x16x32_bf16 v[52:55], v[144:147], v[198:201], 0
	v_mfma_f32_16x16x32_bf16 v[48:51], v[174:177], v[198:201], 0
	v_mfma_f32_16x16x32_bf16 v[36:39], v[144:147], v[206:209], 0
	v_mfma_f32_16x16x32_bf16 v[32:35], v[174:177], v[206:209], 0
	v_mfma_f32_16x16x32_bf16 v[84:87], v[148:151], v[186:189], v[84:87]
	v_mfma_f32_16x16x32_bf16 v[80:83], v[178:181], v[186:189], v[80:83]
	v_mfma_f32_16x16x32_bf16 v[68:71], v[148:151], v[194:197], v[68:71]
	v_mfma_f32_16x16x32_bf16 v[64:67], v[178:181], v[194:197], v[64:67]
	v_mfma_f32_16x16x32_bf16 v[52:55], v[148:151], v[202:205], v[52:55]
	v_mfma_f32_16x16x32_bf16 v[48:51], v[178:181], v[202:205], v[48:51]
	v_mfma_f32_16x16x32_bf16 v[36:39], v[148:151], v[232:235], v[36:39]
	v_mfma_f32_16x16x32_bf16 v[32:35], v[178:181], v[232:235], v[32:35]
	s_setprio 0
	s_barrier
	v_add_u32_e32 v140, 0x18000, v227
	v_add_u32_e32 v152, 0x1c000, v227
	ds_read_b128 v[128:131], v140
	ds_read_b128 v[132:135], v140 offset:1024
	ds_read_b128 v[136:139], v140 offset:2048
	ds_read_b128 v[140:143], v140 offset:3072
	ds_read_b128 v[144:147], v152
	ds_read_b128 v[148:151], v152 offset:1024
	ds_read_b128 v[174:177], v152 offset:2048
	ds_read_b128 v[178:181], v152 offset:3072
	s_add_u32 s46, s46, s26
	s_addc_u32 s47, s47, 0
	s_mov_b32 m0, s8
	ds_read_b128 v[182:185], v230 offset:32768
	ds_read_b128 v[186:189], v230 offset:33792
	ds_read_b128 v[190:193], v230 offset:34816
	ds_read_b128 v[194:197], v230 offset:35840
	ds_read_b128 v[198:201], v230 offset:36864
	ds_read_b128 v[202:205], v230 offset:37888
	ds_read_b128 v[206:209], v230 offset:38912
	ds_read_b128 v[232:235], v230 offset:39936
	global_load_lds_dwordx4 v158, s[46:47]
	s_mov_b32 m0, s9
	s_nop 0
	global_load_lds_dwordx4 v162, s[46:47]
	s_waitcnt vmcnt(8)
	s_waitcnt lgkmcnt(0)
	s_barrier
	s_setprio 1
	s_waitcnt lgkmcnt(0)
	v_mfma_f32_16x16x32_bf16 v[16:19], v[128:131], v[182:185], v[16:19]
	v_mfma_f32_16x16x32_bf16 v[28:31], v[136:139], v[182:185], v[28:31]
	v_mfma_f32_16x16x32_bf16 v[12:15], v[128:131], v[190:193], v[12:15]
	v_mfma_f32_16x16x32_bf16 v[8:11], v[136:139], v[190:193], v[8:11]
	v_mfma_f32_16x16x32_bf16 v[124:127], v[128:131], v[198:201], v[124:127]
	v_mfma_f32_16x16x32_bf16 v[120:123], v[136:139], v[198:201], v[120:123]
	v_mfma_f32_16x16x32_bf16 v[108:111], v[128:131], v[206:209], v[108:111]
	v_mfma_f32_16x16x32_bf16 v[104:107], v[136:139], v[206:209], v[104:107]
	v_mfma_f32_16x16x32_bf16 v[16:19], v[132:135], v[186:189], v[16:19]
	v_mfma_f32_16x16x32_bf16 v[28:31], v[140:143], v[186:189], v[28:31]
	v_mfma_f32_16x16x32_bf16 v[12:15], v[132:135], v[194:197], v[12:15]
	v_mfma_f32_16x16x32_bf16 v[8:11], v[140:143], v[194:197], v[8:11]
	v_mfma_f32_16x16x32_bf16 v[124:127], v[132:135], v[202:205], v[124:127]
	v_mfma_f32_16x16x32_bf16 v[120:123], v[140:143], v[202:205], v[120:123]
	v_mfma_f32_16x16x32_bf16 v[108:111], v[132:135], v[232:235], v[108:111]
	v_mfma_f32_16x16x32_bf16 v[104:107], v[140:143], v[232:235], v[104:107]
	s_setprio 0
	s_setprio 1
	v_mfma_f32_16x16x32_bf16 v[24:27], v[144:147], v[182:185], v[24:27]
	v_mfma_f32_16x16x32_bf16 v[20:23], v[174:177], v[182:185], v[20:23]
	v_mfma_f32_16x16x32_bf16 v[4:7], v[144:147], v[190:193], v[4:7]
	v_mfma_f32_16x16x32_bf16 v[0:3], v[174:177], v[190:193], v[0:3]
	v_mfma_f32_16x16x32_bf16 v[116:119], v[144:147], v[198:201], v[116:119]
	v_mfma_f32_16x16x32_bf16 v[112:115], v[174:177], v[198:201], v[112:115]
	v_mfma_f32_16x16x32_bf16 v[100:103], v[144:147], v[206:209], v[100:103]
	v_mfma_f32_16x16x32_bf16 v[96:99], v[174:177], v[206:209], v[96:99]
	v_mfma_f32_16x16x32_bf16 v[24:27], v[148:151], v[186:189], v[24:27]
	v_mfma_f32_16x16x32_bf16 v[20:23], v[178:181], v[186:189], v[20:23]
	v_mfma_f32_16x16x32_bf16 v[4:7], v[148:151], v[194:197], v[4:7]
	v_mfma_f32_16x16x32_bf16 v[0:3], v[178:181], v[194:197], v[0:3]
	v_mfma_f32_16x16x32_bf16 v[116:119], v[148:151], v[202:205], v[116:119]
	v_mfma_f32_16x16x32_bf16 v[112:115], v[178:181], v[202:205], v[112:115]
	v_mfma_f32_16x16x32_bf16 v[100:103], v[148:151], v[232:235], v[100:103]
	v_mfma_f32_16x16x32_bf16 v[96:99], v[178:181], v[232:235], v[96:99]
	s_setprio 0
	s_barrier
	s_add_u32 vcc_lo, s70, s6
	s_addc_u32 vcc_hi, s71, s7
	s_sub_u32 vcc_lo, vcc_lo, s26
	s_subb_u32 vcc_hi, vcc_hi, 0
	s_add_i32 m0, s3, 0x18000
	ds_read_b128 v[182:185], v230 offset:49152
	ds_read_b128 v[186:189], v230 offset:50176
	ds_read_b128 v[190:193], v230 offset:51200
	ds_read_b128 v[194:197], v230 offset:52224
	ds_read_b128 v[198:201], v230 offset:53248
	ds_read_b128 v[202:205], v230 offset:54272
	ds_read_b128 v[206:209], v230 offset:55296
	ds_read_b128 v[232:235], v230 offset:56320
	global_load_lds_dwordx4 v160, vcc
	s_add_i32 m0, s3, 0x1a000
	s_nop 0
	global_load_lds_dwordx4 v164, vcc
	s_add_u32 vcc_lo, vcc_lo, s26
	s_addc_u32 vcc_hi, vcc_hi, 0
	s_add_i32 m0, s3, 0x1c000
	s_nop 0
	global_load_lds_dwordx4 v160, vcc
	s_add_i32 m0, s3, 0x1e000
	s_nop 0
	global_load_lds_dwordx4 v164, vcc
	s_add_u32 vcc_lo, s46, s6
	s_addc_u32 vcc_hi, s47, s7
	s_sub_u32 vcc_lo, vcc_lo, s26
	s_subb_u32 vcc_hi, vcc_hi, 0
	s_mov_b32 m0, s30
	s_nop 0
	global_load_lds_dwordx4 v158, vcc
	s_mov_b32 m0, s31
	s_nop 0
	global_load_lds_dwordx4 v162, vcc
	s_waitcnt vmcnt(8)
	s_waitcnt lgkmcnt(0)
	s_barrier
	s_setprio 1
	s_waitcnt lgkmcnt(0)
	v_mfma_f32_16x16x32_bf16 v[92:95], v[128:131], v[182:185], v[92:95]
	v_mfma_f32_16x16x32_bf16 v[88:91], v[136:139], v[182:185], v[88:91]
	v_mfma_f32_16x16x32_bf16 v[76:79], v[128:131], v[190:193], v[76:79]
	v_mfma_f32_16x16x32_bf16 v[72:75], v[136:139], v[190:193], v[72:75]
	v_mfma_f32_16x16x32_bf16 v[60:63], v[128:131], v[198:201], v[60:63]
	v_mfma_f32_16x16x32_bf16 v[56:59], v[136:139], v[198:201], v[56:59]
	v_mfma_f32_16x16x32_bf16 v[44:47], v[128:131], v[206:209], v[44:47]
	v_mfma_f32_16x16x32_bf16 v[40:43], v[136:139], v[206:209], v[40:43]
	v_mfma_f32_16x16x32_bf16 v[92:95], v[132:135], v[186:189], v[92:95]
	v_mfma_f32_16x16x32_bf16 v[88:91], v[140:143], v[186:189], v[88:91]
	v_mfma_f32_16x16x32_bf16 v[76:79], v[132:135], v[194:197], v[76:79]
	v_mfma_f32_16x16x32_bf16 v[72:75], v[140:143], v[194:197], v[72:75]
	v_mfma_f32_16x16x32_bf16 v[60:63], v[132:135], v[202:205], v[60:63]
	v_mfma_f32_16x16x32_bf16 v[56:59], v[140:143], v[202:205], v[56:59]
	v_mfma_f32_16x16x32_bf16 v[44:47], v[132:135], v[232:235], v[44:47]
	v_mfma_f32_16x16x32_bf16 v[40:43], v[140:143], v[232:235], v[40:43]
	s_setprio 0
	s_setprio 1
	v_mfma_f32_16x16x32_bf16 v[84:87], v[144:147], v[182:185], v[84:87]
	v_mfma_f32_16x16x32_bf16 v[80:83], v[174:177], v[182:185], v[80:83]
	v_mfma_f32_16x16x32_bf16 v[68:71], v[144:147], v[190:193], v[68:71]
	v_mfma_f32_16x16x32_bf16 v[64:67], v[174:177], v[190:193], v[64:67]
	v_mfma_f32_16x16x32_bf16 v[52:55], v[144:147], v[198:201], v[52:55]
	v_mfma_f32_16x16x32_bf16 v[48:51], v[174:177], v[198:201], v[48:51]
	v_mfma_f32_16x16x32_bf16 v[36:39], v[144:147], v[206:209], v[36:39]
	v_mfma_f32_16x16x32_bf16 v[32:35], v[174:177], v[206:209], v[32:35]
	v_mfma_f32_16x16x32_bf16 v[84:87], v[148:151], v[186:189], v[84:87]
	v_mfma_f32_16x16x32_bf16 v[80:83], v[178:181], v[186:189], v[80:83]
	v_mfma_f32_16x16x32_bf16 v[68:71], v[148:151], v[194:197], v[68:71]
	v_mfma_f32_16x16x32_bf16 v[64:67], v[178:181], v[194:197], v[64:67]
	v_mfma_f32_16x16x32_bf16 v[52:55], v[148:151], v[202:205], v[52:55]
	v_mfma_f32_16x16x32_bf16 v[48:51], v[178:181], v[202:205], v[48:51]
	v_mfma_f32_16x16x32_bf16 v[36:39], v[148:151], v[232:235], v[36:39]
	v_mfma_f32_16x16x32_bf16 v[32:35], v[178:181], v[232:235], v[32:35]
	s_setprio 0
	s_barrier
	s_add_u32 s44, s44, 0x100
	s_addc_u32 s45, s45, 0
	s_add_u32 s23, s23, 0x100
	s_addc_u32 s48, s48, 0
	s_cmp_ge_u32 s49, s88
	s_mov_b32 s46, s49
	s_cbranch_scc1 .LBB0_249
.LBB0_248:
	s_add_i32 s49, s46, 2
	s_add_u32 s69, s44, 0x80
	s_addc_u32 s47, s45, 0
	s_add_i32 s80, 0, 0x10000
	s_cmp_eq_u32 s90, s46
	s_cselect_b32 s47, s65, s47
	s_cselect_b32 s46, s64, s69
	s_cselect_b32 s71, s67, s48
	s_cselect_b32 s70, s66, s23
	s_add_i32 s69, 0, 0x14000
	v_add_u32_e32 v140, s80, v227
	v_add_u32_e32 v152, s69, v227
	ds_read_b128 v[128:131], v140
	ds_read_b128 v[132:135], v140 offset:1024
	ds_read_b128 v[136:139], v140 offset:2048
	ds_read_b128 v[140:143], v140 offset:3072
	ds_read_b128 v[144:147], v152
	ds_read_b128 v[148:151], v152 offset:1024
	ds_read_b128 v[174:177], v152 offset:2048
	ds_read_b128 v[178:181], v152 offset:3072
	s_add_i32 m0, s50, 0xc000
	ds_read_b128 v[182:185], v230
	ds_read_b128 v[186:189], v230 offset:1024
	ds_read_b128 v[190:193], v230 offset:2048
	ds_read_b128 v[194:197], v230 offset:3072
	ds_read_b128 v[198:201], v230 offset:4096
	ds_read_b128 v[202:205], v230 offset:5120
	ds_read_b128 v[206:209], v230 offset:6144
	ds_read_b128 v[232:235], v230 offset:7168
	global_load_lds_dwordx4 v170, s[44:45]
	s_add_i32 m0, s50, 0xe000
	s_nop 0
	global_load_lds_dwordx4 v172, s[44:45]
	s_waitcnt vmcnt(8)
	s_waitcnt lgkmcnt(0)
	s_barrier
	s_setprio 1
	s_waitcnt lgkmcnt(0)
	v_mfma_f32_16x16x32_bf16 v[16:19], v[128:131], v[182:185], v[16:19]
	v_mfma_f32_16x16x32_bf16 v[28:31], v[136:139], v[182:185], v[28:31]
	v_mfma_f32_16x16x32_bf16 v[12:15], v[128:131], v[190:193], v[12:15]
	v_mfma_f32_16x16x32_bf16 v[8:11], v[136:139], v[190:193], v[8:11]
	v_mfma_f32_16x16x32_bf16 v[124:127], v[128:131], v[198:201], v[124:127]
	v_mfma_f32_16x16x32_bf16 v[120:123], v[136:139], v[198:201], v[120:123]
	v_mfma_f32_16x16x32_bf16 v[108:111], v[128:131], v[206:209], v[108:111]
	v_mfma_f32_16x16x32_bf16 v[104:107], v[136:139], v[206:209], v[104:107]
	v_mfma_f32_16x16x32_bf16 v[16:19], v[132:135], v[186:189], v[16:19]
	v_mfma_f32_16x16x32_bf16 v[28:31], v[140:143], v[186:189], v[28:31]
	v_mfma_f32_16x16x32_bf16 v[12:15], v[132:135], v[194:197], v[12:15]
	v_mfma_f32_16x16x32_bf16 v[8:11], v[140:143], v[194:197], v[8:11]
	v_mfma_f32_16x16x32_bf16 v[124:127], v[132:135], v[202:205], v[124:127]
	v_mfma_f32_16x16x32_bf16 v[120:123], v[140:143], v[202:205], v[120:123]
	v_mfma_f32_16x16x32_bf16 v[108:111], v[132:135], v[232:235], v[108:111]
	v_mfma_f32_16x16x32_bf16 v[104:107], v[140:143], v[232:235], v[104:107]
	s_setprio 0
	s_setprio 1
	v_mfma_f32_16x16x32_bf16 v[24:27], v[144:147], v[182:185], v[24:27]
	v_mfma_f32_16x16x32_bf16 v[20:23], v[174:177], v[182:185], v[20:23]
	v_mfma_f32_16x16x32_bf16 v[4:7], v[144:147], v[190:193], v[4:7]
	v_mfma_f32_16x16x32_bf16 v[0:3], v[174:177], v[190:193], v[0:3]
	v_mfma_f32_16x16x32_bf16 v[116:119], v[144:147], v[198:201], v[116:119]
	v_mfma_f32_16x16x32_bf16 v[112:115], v[174:177], v[198:201], v[112:115]
	v_mfma_f32_16x16x32_bf16 v[100:103], v[144:147], v[206:209], v[100:103]
	v_mfma_f32_16x16x32_bf16 v[96:99], v[174:177], v[206:209], v[96:99]
	v_mfma_f32_16x16x32_bf16 v[24:27], v[148:151], v[186:189], v[24:27]
	v_mfma_f32_16x16x32_bf16 v[20:23], v[178:181], v[186:189], v[20:23]
	v_mfma_f32_16x16x32_bf16 v[4:7], v[148:151], v[194:197], v[4:7]
	v_mfma_f32_16x16x32_bf16 v[0:3], v[178:181], v[194:197], v[0:3]
	v_mfma_f32_16x16x32_bf16 v[116:119], v[148:151], v[202:205], v[116:119]
	v_mfma_f32_16x16x32_bf16 v[112:115], v[178:181], v[202:205], v[112:115]
	v_mfma_f32_16x16x32_bf16 v[100:103], v[148:151], v[232:235], v[100:103]
	v_mfma_f32_16x16x32_bf16 v[96:99], v[178:181], v[232:235], v[96:99]
	s_setprio 0
	s_barrier
	s_add_i32 s80, s80, s3
	s_mov_b32 m0, s80
	ds_read_b128 v[182:185], v230 offset:16384
	ds_read_b128 v[186:189], v230 offset:17408
	ds_read_b128 v[190:193], v230 offset:18432
	ds_read_b128 v[194:197], v230 offset:19456
	ds_read_b128 v[198:201], v230 offset:20480
	ds_read_b128 v[202:205], v230 offset:21504
	ds_read_b128 v[206:209], v230 offset:22528
	ds_read_b128 v[232:235], v230 offset:23552
	global_load_lds_dwordx4 v160, s[70:71]
	s_add_i32 m0, s80, 0x2000
	s_add_i32 s69, s69, s3
	global_load_lds_dwordx4 v164, s[70:71]
	s_add_u32 s70, s70, s26
	s_addc_u32 s71, s71, 0
	s_mov_b32 m0, s69
	s_nop 0
	global_load_lds_dwordx4 v160, s[70:71]
	s_add_i32 m0, s69, 0x2000
	s_nop 0
	global_load_lds_dwordx4 v164, s[70:71]
	s_mov_b32 m0, s50
	s_nop 0
	global_load_lds_dwordx4 v158, s[46:47]
	s_mov_b32 m0, s51
	s_nop 0
	global_load_lds_dwordx4 v162, s[46:47]
	s_waitcnt vmcnt(8)
	s_waitcnt lgkmcnt(0)
	s_barrier
	s_setprio 1
	s_waitcnt lgkmcnt(0)
	v_mfma_f32_16x16x32_bf16 v[92:95], v[128:131], v[182:185], v[92:95]
	v_mfma_f32_16x16x32_bf16 v[88:91], v[136:139], v[182:185], v[88:91]
	v_mfma_f32_16x16x32_bf16 v[76:79], v[128:131], v[190:193], v[76:79]
	v_mfma_f32_16x16x32_bf16 v[72:75], v[136:139], v[190:193], v[72:75]
	v_mfma_f32_16x16x32_bf16 v[60:63], v[128:131], v[198:201], v[60:63]
	v_mfma_f32_16x16x32_bf16 v[56:59], v[136:139], v[198:201], v[56:59]
	v_mfma_f32_16x16x32_bf16 v[44:47], v[128:131], v[206:209], v[44:47]
	v_mfma_f32_16x16x32_bf16 v[40:43], v[136:139], v[206:209], v[40:43]
	v_mfma_f32_16x16x32_bf16 v[92:95], v[132:135], v[186:189], v[92:95]
	v_mfma_f32_16x16x32_bf16 v[88:91], v[140:143], v[186:189], v[88:91]
	v_mfma_f32_16x16x32_bf16 v[76:79], v[132:135], v[194:197], v[76:79]
	v_mfma_f32_16x16x32_bf16 v[72:75], v[140:143], v[194:197], v[72:75]
	v_mfma_f32_16x16x32_bf16 v[60:63], v[132:135], v[202:205], v[60:63]
	v_mfma_f32_16x16x32_bf16 v[56:59], v[140:143], v[202:205], v[56:59]
	v_mfma_f32_16x16x32_bf16 v[44:47], v[132:135], v[232:235], v[44:47]
	v_mfma_f32_16x16x32_bf16 v[40:43], v[140:143], v[232:235], v[40:43]
	s_setprio 0
	s_setprio 1
	v_mfma_f32_16x16x32_bf16 v[84:87], v[144:147], v[182:185], v[84:87]
	v_mfma_f32_16x16x32_bf16 v[80:83], v[174:177], v[182:185], v[80:83]
	v_mfma_f32_16x16x32_bf16 v[68:71], v[144:147], v[190:193], v[68:71]
	v_mfma_f32_16x16x32_bf16 v[64:67], v[174:177], v[190:193], v[64:67]
	v_mfma_f32_16x16x32_bf16 v[52:55], v[144:147], v[198:201], v[52:55]
	v_mfma_f32_16x16x32_bf16 v[48:51], v[174:177], v[198:201], v[48:51]
	v_mfma_f32_16x16x32_bf16 v[36:39], v[144:147], v[206:209], v[36:39]
	v_mfma_f32_16x16x32_bf16 v[32:35], v[174:177], v[206:209], v[32:35]
	v_mfma_f32_16x16x32_bf16 v[84:87], v[148:151], v[186:189], v[84:87]
	v_mfma_f32_16x16x32_bf16 v[80:83], v[178:181], v[186:189], v[80:83]
	v_mfma_f32_16x16x32_bf16 v[68:71], v[148:151], v[194:197], v[68:71]
	v_mfma_f32_16x16x32_bf16 v[64:67], v[178:181], v[194:197], v[64:67]
	v_mfma_f32_16x16x32_bf16 v[52:55], v[148:151], v[202:205], v[52:55]
	v_mfma_f32_16x16x32_bf16 v[48:51], v[178:181], v[202:205], v[48:51]
	v_mfma_f32_16x16x32_bf16 v[36:39], v[148:151], v[232:235], v[36:39]
	v_mfma_f32_16x16x32_bf16 v[32:35], v[178:181], v[232:235], v[32:35]
	s_setprio 0
	s_barrier
	v_add_u32_e32 v140, 0x18000, v227
	v_add_u32_e32 v152, 0x1c000, v227
	ds_read_b128 v[128:131], v140
	ds_read_b128 v[132:135], v140 offset:1024
	ds_read_b128 v[136:139], v140 offset:2048
	ds_read_b128 v[140:143], v140 offset:3072
	ds_read_b128 v[144:147], v152
	ds_read_b128 v[148:151], v152 offset:1024
	ds_read_b128 v[174:177], v152 offset:2048
	ds_read_b128 v[178:181], v152 offset:3072
	s_add_u32 s46, s46, s26
	s_addc_u32 s47, s47, 0
	s_mov_b32 m0, s8
	ds_read_b128 v[182:185], v230 offset:32768
	ds_read_b128 v[186:189], v230 offset:33792
	ds_read_b128 v[190:193], v230 offset:34816
	ds_read_b128 v[194:197], v230 offset:35840
	ds_read_b128 v[198:201], v230 offset:36864
	ds_read_b128 v[202:205], v230 offset:37888
	ds_read_b128 v[206:209], v230 offset:38912
	ds_read_b128 v[232:235], v230 offset:39936
	global_load_lds_dwordx4 v158, s[46:47]
	s_mov_b32 m0, s9
	s_nop 0
	global_load_lds_dwordx4 v162, s[46:47]
	s_waitcnt vmcnt(8)
	s_waitcnt lgkmcnt(0)
	s_barrier
	s_setprio 1
	s_waitcnt lgkmcnt(0)
	v_mfma_f32_16x16x32_bf16 v[16:19], v[128:131], v[182:185], v[16:19]
	v_mfma_f32_16x16x32_bf16 v[28:31], v[136:139], v[182:185], v[28:31]
	v_mfma_f32_16x16x32_bf16 v[12:15], v[128:131], v[190:193], v[12:15]
	v_mfma_f32_16x16x32_bf16 v[8:11], v[136:139], v[190:193], v[8:11]
	v_mfma_f32_16x16x32_bf16 v[124:127], v[128:131], v[198:201], v[124:127]
	v_mfma_f32_16x16x32_bf16 v[120:123], v[136:139], v[198:201], v[120:123]
	v_mfma_f32_16x16x32_bf16 v[108:111], v[128:131], v[206:209], v[108:111]
	v_mfma_f32_16x16x32_bf16 v[104:107], v[136:139], v[206:209], v[104:107]
	v_mfma_f32_16x16x32_bf16 v[16:19], v[132:135], v[186:189], v[16:19]
	v_mfma_f32_16x16x32_bf16 v[28:31], v[140:143], v[186:189], v[28:31]
	v_mfma_f32_16x16x32_bf16 v[12:15], v[132:135], v[194:197], v[12:15]
	v_mfma_f32_16x16x32_bf16 v[8:11], v[140:143], v[194:197], v[8:11]
	v_mfma_f32_16x16x32_bf16 v[124:127], v[132:135], v[202:205], v[124:127]
	v_mfma_f32_16x16x32_bf16 v[120:123], v[140:143], v[202:205], v[120:123]
	v_mfma_f32_16x16x32_bf16 v[108:111], v[132:135], v[232:235], v[108:111]
	v_mfma_f32_16x16x32_bf16 v[104:107], v[140:143], v[232:235], v[104:107]
	s_setprio 0
	s_setprio 1
	v_mfma_f32_16x16x32_bf16 v[24:27], v[144:147], v[182:185], v[24:27]
	v_mfma_f32_16x16x32_bf16 v[20:23], v[174:177], v[182:185], v[20:23]
	v_mfma_f32_16x16x32_bf16 v[4:7], v[144:147], v[190:193], v[4:7]
	v_mfma_f32_16x16x32_bf16 v[0:3], v[174:177], v[190:193], v[0:3]
	v_mfma_f32_16x16x32_bf16 v[116:119], v[144:147], v[198:201], v[116:119]
	v_mfma_f32_16x16x32_bf16 v[112:115], v[174:177], v[198:201], v[112:115]
	v_mfma_f32_16x16x32_bf16 v[100:103], v[144:147], v[206:209], v[100:103]
	v_mfma_f32_16x16x32_bf16 v[96:99], v[174:177], v[206:209], v[96:99]
	v_mfma_f32_16x16x32_bf16 v[24:27], v[148:151], v[186:189], v[24:27]
	v_mfma_f32_16x16x32_bf16 v[20:23], v[178:181], v[186:189], v[20:23]
	v_mfma_f32_16x16x32_bf16 v[4:7], v[148:151], v[194:197], v[4:7]
	v_mfma_f32_16x16x32_bf16 v[0:3], v[178:181], v[194:197], v[0:3]
	v_mfma_f32_16x16x32_bf16 v[116:119], v[148:151], v[202:205], v[116:119]
	v_mfma_f32_16x16x32_bf16 v[112:115], v[178:181], v[202:205], v[112:115]
	v_mfma_f32_16x16x32_bf16 v[100:103], v[148:151], v[232:235], v[100:103]
	v_mfma_f32_16x16x32_bf16 v[96:99], v[178:181], v[232:235], v[96:99]
	s_setprio 0
	s_barrier
	s_add_u32 vcc_lo, s70, s6
	s_addc_u32 vcc_hi, s71, s7
	s_sub_u32 vcc_lo, vcc_lo, s26
	s_subb_u32 vcc_hi, vcc_hi, 0
	s_add_i32 m0, s3, 0x18000
	ds_read_b128 v[182:185], v230 offset:49152
	ds_read_b128 v[186:189], v230 offset:50176
	ds_read_b128 v[190:193], v230 offset:51200
	ds_read_b128 v[194:197], v230 offset:52224
	ds_read_b128 v[198:201], v230 offset:53248
	ds_read_b128 v[202:205], v230 offset:54272
	ds_read_b128 v[206:209], v230 offset:55296
	ds_read_b128 v[232:235], v230 offset:56320
	global_load_lds_dwordx4 v160, vcc
	s_add_i32 m0, s3, 0x1a000
	s_nop 0
	global_load_lds_dwordx4 v164, vcc
	s_add_u32 vcc_lo, vcc_lo, s26
	s_addc_u32 vcc_hi, vcc_hi, 0
	s_add_i32 m0, s3, 0x1c000
	s_nop 0
	global_load_lds_dwordx4 v160, vcc
	s_add_i32 m0, s3, 0x1e000
	s_nop 0
	global_load_lds_dwordx4 v164, vcc
	s_add_u32 vcc_lo, s46, s6
	s_addc_u32 vcc_hi, s47, s7
	s_sub_u32 vcc_lo, vcc_lo, s26
	s_subb_u32 vcc_hi, vcc_hi, 0
	s_mov_b32 m0, s30
	s_nop 0
	global_load_lds_dwordx4 v158, vcc
	s_mov_b32 m0, s31
	s_nop 0
	global_load_lds_dwordx4 v162, vcc
	s_waitcnt vmcnt(8)
	s_waitcnt lgkmcnt(0)
	s_barrier
	s_setprio 1
	s_waitcnt lgkmcnt(0)
	v_mfma_f32_16x16x32_bf16 v[92:95], v[128:131], v[182:185], v[92:95]
	v_mfma_f32_16x16x32_bf16 v[88:91], v[136:139], v[182:185], v[88:91]
	v_mfma_f32_16x16x32_bf16 v[76:79], v[128:131], v[190:193], v[76:79]
	v_mfma_f32_16x16x32_bf16 v[72:75], v[136:139], v[190:193], v[72:75]
	v_mfma_f32_16x16x32_bf16 v[60:63], v[128:131], v[198:201], v[60:63]
	v_mfma_f32_16x16x32_bf16 v[56:59], v[136:139], v[198:201], v[56:59]
	v_mfma_f32_16x16x32_bf16 v[44:47], v[128:131], v[206:209], v[44:47]
	v_mfma_f32_16x16x32_bf16 v[40:43], v[136:139], v[206:209], v[40:43]
	v_mfma_f32_16x16x32_bf16 v[92:95], v[132:135], v[186:189], v[92:95]
	v_mfma_f32_16x16x32_bf16 v[88:91], v[140:143], v[186:189], v[88:91]
	v_mfma_f32_16x16x32_bf16 v[76:79], v[132:135], v[194:197], v[76:79]
	v_mfma_f32_16x16x32_bf16 v[72:75], v[140:143], v[194:197], v[72:75]
	v_mfma_f32_16x16x32_bf16 v[60:63], v[132:135], v[202:205], v[60:63]
	v_mfma_f32_16x16x32_bf16 v[56:59], v[140:143], v[202:205], v[56:59]
	v_mfma_f32_16x16x32_bf16 v[44:47], v[132:135], v[232:235], v[44:47]
	v_mfma_f32_16x16x32_bf16 v[40:43], v[140:143], v[232:235], v[40:43]
	s_setprio 0
	s_setprio 1
	v_mfma_f32_16x16x32_bf16 v[84:87], v[144:147], v[182:185], v[84:87]
	v_mfma_f32_16x16x32_bf16 v[80:83], v[174:177], v[182:185], v[80:83]
	v_mfma_f32_16x16x32_bf16 v[68:71], v[144:147], v[190:193], v[68:71]
	v_mfma_f32_16x16x32_bf16 v[64:67], v[174:177], v[190:193], v[64:67]
	v_mfma_f32_16x16x32_bf16 v[52:55], v[144:147], v[198:201], v[52:55]
	v_mfma_f32_16x16x32_bf16 v[48:51], v[174:177], v[198:201], v[48:51]
	v_mfma_f32_16x16x32_bf16 v[36:39], v[144:147], v[206:209], v[36:39]
	v_mfma_f32_16x16x32_bf16 v[32:35], v[174:177], v[206:209], v[32:35]
	v_mfma_f32_16x16x32_bf16 v[84:87], v[148:151], v[186:189], v[84:87]
	v_mfma_f32_16x16x32_bf16 v[80:83], v[178:181], v[186:189], v[80:83]
	v_mfma_f32_16x16x32_bf16 v[68:71], v[148:151], v[194:197], v[68:71]
	v_mfma_f32_16x16x32_bf16 v[64:67], v[178:181], v[194:197], v[64:67]
	v_mfma_f32_16x16x32_bf16 v[52:55], v[148:151], v[202:205], v[52:55]
	v_mfma_f32_16x16x32_bf16 v[48:51], v[178:181], v[202:205], v[48:51]
	v_mfma_f32_16x16x32_bf16 v[36:39], v[148:151], v[232:235], v[36:39]
	v_mfma_f32_16x16x32_bf16 v[32:35], v[178:181], v[232:235], v[32:35]
	s_setprio 0
	s_barrier
	s_add_u32 s44, s44, 0x100
	s_addc_u32 s45, s45, 0
	s_add_u32 s23, s23, 0x100
	s_addc_u32 s48, s48, 0
	s_cmp_ge_u32 s49, s88
	s_mov_b32 s46, s49
	s_cbranch_scc0 .LBB0_248
.LBB0_249:
	s_add_i32 s69, 0, 0x18000
	s_add_i32 s70, 0, 0x1c000
	s_and_b64 vcc, exec, s[28:29]
	s_cbranch_vccnz .LBB0_256
	s_mov_b64 s[44:45], -1
	s_and_b64 vcc, exec, s[34:35]
	s_cbranch_vccnz .LBB0_257
